# attention+S5 pass A phase: sink logit loaded with the unit's first loads (mid-unit vmcnt(0) gone); pass A table row no longer serialises the B-table and u-row loads
# baseline (speedup 1.0000x reference)
; __device__ __forceinline__ int opq(int v) { asm volatile("" : "+v"(v)); return v; }
; template <bool PASS_B> __device__ __forceinline__ void ssm_tables(const Args& a, int l, int gq, int wave, SsmTab& T) {
;     const int lane = opq(threadIdx.x) & 63, r = lane & 15, qd = lane >> 4, g = gq * 8 + wave;
;     T.ta = ((const f32x4*)(a.ws + WS_TA))[(l * NG + g) * NP + lane];
;     const bf16_t* tbh = (const bf16_t*)(a.ws + WS_TB) + (size_t)(l * NG + g) * 128 * GC + r * GC + 8 * (qd & 1);
; #pragma unroll
;     for (int pt = 0; pt < 8; ++pt) { const bf16x8 v = *(const bf16x8*)(tbh + pt * 16 * GC); T.af[pt] = qd < 2 ? v : (bf16x8){0, 0, 0, 0, 0, 0, 0, 0}; }
.LBB0_329:
	s_lshl_b32 s0, s14, 5
	v_readlane_b32 s1, v253, 44
	s_add_i32 s26, s1, s0
	v_mov_b32_e32 v20, v184
	s_lshl_b32 s62, s26, 6
	v_readlane_b32 s0, v253, 36
	v_and_b32_e32 v21, 63, v20
	v_or_b32_e32 v0, s62, v21
	v_readlane_b32 s1, v253, 37
	s_lshl_b64 s[6:7], s[26:27], 12
	s_mov_b32 s4, s14
	v_lshl_add_u64 v[2:3], v[0:1], 4, s[0:1]
	global_load_dwordx4 v[240:243], v[2:3], off
	v_readlane_b32 s0, v253, 38
	s_add_u32 s8, s0, s6
	v_readlane_b32 s0, v253, 39
	v_lshlrev_b32_e32 v0, 5, v20
	s_mov_b32 s5, s27
	s_addc_u32 s9, s0, s7
	v_and_b32_e32 v0, 0x1e0, v0
	v_writelane_b32 v255, s4, 41
	v_lshl_add_u64 v[2:3], s[8:9], 0, v[0:1]
	v_and_b32_e32 v0, 16, v20
	v_writelane_b32 v255, s5, 42
	v_lshl_add_u64 v[2:3], v[2:3], 0, v[0:1]
	v_cmp_gt_u32_e32 vcc, 32, v21
	s_nop 0
	v_mov_b32_e32 v30, 0
	v_mov_b32_e32 v34, 0
	v_mov_b32_e32 v35, 0
	v_mov_b32_e32 v36, 0
	v_mov_b32_e32 v37, 0
	v_mov_b32_e32 v38, 0
	v_mov_b32_e32 v39, 0
	v_mov_b32_e32 v40, 0
	v_mov_b32_e32 v41, 0
	s_and_saveexec_b64 s[0:1], vcc
	s_cbranch_execz .LBB0_331
	global_load_dwordx4 v[34:37], v[2:3], off
	global_load_dwordx4 v[38:41], v[2:3], off offset:512

; #define LAS __attribute__((address_space(3)))
; template <bool PASS_B> __device__ __forceinline__ void ssm_unit(const Args& a, LAS unsigned char* lds, const SsmTab& T, const u32x4 (&pre)[2], int l, size_t row0, int ntok, int gq, float& hr_io, float& hi_io, int wave) {
;     ...
;     const f32x4 ta = T.ta; const float ar = ta[0], ai = ta[1], dsk = T.dsk;
;     float hr = hr_io, hi = hi_io;
; #pragma unroll
;     for (int k = 0; k < 2; ++k) { const int idx = tid + 512 * k, t = idx >> 4, c8 = idx & 15; if (idx < ntok * 16) *(LAS u32x4*)(Ub + t * UST + c8 * 8) = pre[k]; }
;     __syncthreads();
; #pragma unroll 1
;     for (int t0 = 0; t0 < ntok; t0 += 16) {
;         const int nt = (ntok - t0) < 16 ? (ntok - t0) : 16;
;         {
;             const bf16x8 uv = *(const LAS bf16x8*)(Ub + (t0 + r) * UST + wave * 16 + 8 * (qd & 1)); const bf16x8 ub = qd < 2 ? uv : (bf16x8){0, 0, 0, 0, 0, 0, 0, 0};
; #pragma unroll
;             for (int pt = 0; pt < 8; ++pt) { const f32x4 x = __builtin_amdgcn_mfma_f32_16x16x32_bf16(T.af[pt], ub, (f32x4){0.f, 0.f, 0.f, 0.f}, 0, 0, 0); *(LAS f32x4*)(Xs + r * XST + pt * 16 + 4 * qd) = x; }
;         }
;         asm volatile("s_waitcnt lgkmcnt(0)" ::: "memory");
;         {
;             typedef float f32x2 __attribute__((ext_vector_type(2)));
;             f32x2 xv[16];
; #pragma unroll
;             for (int tt = 0; tt < 16; ++tt) xv[tt] = *(const LAS f32x2*)(Xs + tt * XST + 2 * lane);
;             f32x2 h = {hr, hi}; const f32x2 a1 = {ar, ar}, a2 = {-ai, ai};
.LBB0_337:
	s_or_b64 exec, exec, s[0:1]
	v_readlane_b32 s0, v253, 40
	v_readlane_b32 s1, v253, 41
	s_andn2_b64 vcc, exec, s[0:1]
	s_cbranch_vccnz .LBB0_360
	s_mov_b32 s18, s2

; template <bool PASS_B> __device__ __forceinline__ void ssm_unit(const Args& a, LAS unsigned char* lds, const SsmTab& T, const u32x4 (&pre)[2], int l, size_t row0, int ntok, int gq, float& hr_io, float& hi_io, int wave) {
;     ...
;             f32x2 h = {hr, hi}; const f32x2 a1 = {ar, ar}, a2 = {-ai, ai};
;             if (nt == 16) {
; #pragma unroll
;                 for (int tt = 0; tt < 16; ++tt) { const f32x2 hs = {h.y, h.x}; h = a1 * h + (a2 * hs + xv[tt]);
.LBB0_343:
	s_or_b64 exec, exec, s[14:15]
	v_mov_b32_e32 v62, 0
	s_waitcnt vmcnt(0)
	v_mov_b32_e32 v2, v240
	v_mov_b32_e32 v3, v240
	v_xor_b32_e32 v28, 0x80000000, v241
	v_mov_b32_e32 v29, v241
	v_mov_b64_e32 v[26:27], v[10:11]
	s_mov_b32 s23, 0
	v_mov_b64_e32 v[24:25], v[8:9]
	v_mov_b64_e32 v[22:23], v[6:7]
	v_mov_b64_e32 v[20:21], v[4:5]
	v_mov_b32_e32 v63, v62
	s_mov_b32 s14, s23
	s_add_i32 s23, s23, 1
	s_cmp_eq_u32 s14, 3
	s_cbranch_scc1 .LBB0_350
	s_branch .LBB0_345

; __device__ __forceinline__ void unpack8(const u32x4 w, float (&f)[8]) { f[0] = bflo(w.x); f[1] = bfhi(w.x); f[2] = bflo(w.y); f[3] = bfhi(w.y); f[4] = bflo(w.z); f[5] = bfhi(w.z); f[6] = bflo(w.w); f[7] = bfhi(w.w); }
; __device__ __forceinline__ void attn_prompt_unit(const Args& a, LAS unsigned char* lds, int l, int b, int qb, int kvh, int tid) {
;     ...
;     const size_t qrow0 = (size_t)b * SEQ + qb * WIN + qh * 64;
;     u32x4 qraw[4][2];
; #pragma unroll
;     for (int qt = 0; qt < 4; ++qt) { const bf16_t* zq = Z + (qrow0 + qt * 16 + r) * INC + ZQ + h * 64 + 8 * qd; qraw[qt][0] = *(const u32x4*)zq; qraw[qt][1] = *(const u32x4*)(zq + 32); }
;     f32x4 gkv[8], gqv[4];
; #pragma unroll
;     for (int c = 0; c < 8; ++c) gkv[c] = *(const f32x4*)(gk + (tid & 1) * 32 + 4 * c);
; #pragma unroll
;     for (int c = 0; c < 4; ++c) gqv[c] = *(const f32x4*)(gq + (c >> 1) * 32 + 8 * qd + 4 * (c & 1));
;     {
;         const int j = tid >> 1, half = tid & 1, pos = (qb - 1) * WIN + j; const bool valid = pos >= 0;
;         float kf[32]; u32x4 vraw[4];
;         if (valid) { const bf16_t* zr = Z + (size_t)(b * SEQ + pos) * INC + kvh * 64 + half * 32;
; #pragma unroll
;             for (int c = 0; c < 4; ++c) { float t8[8]; unpack8(*(const u32x4*)(zr + ZK + c * 8), t8);
; #pragma unroll
;                 for (int k = 0; k < 8; ++k) kf[c * 8 + k] = t8[k];
;                 vraw[c] = *(const u32x4*)(zr + ZV + c * 8); }
;         } else {
; #pragma unroll
;             for (int k = 0; k < 32; ++k) kf[k] = 0.f;
; #pragma unroll
;             for (int c = 0; c < 4; ++c) vraw[c] = (u32x4){0u, 0u, 0u, 0u}; }
;     ...
;     const float cs = 0.125f * LOG2E, sinkl = a.in[I_SINK][l * 8 + h] * LOG2E, slope = exp2f(-(float)(h + 1)) * LOG2E;
.LBB0_364:
	v_mov_b32_e32 v153, v184
	s_and_b32 s11, s10, 1
	s_ashr_i32 s0, s10, 5
	v_ashrrev_i32_e32 v0, 7, v153
	v_lshl_add_u32 v160, s11, 2, v0
	s_bfe_u32 s12, s10, 0x40001
	v_ashrrev_i32_e32 v151, 6, v153
	s_ashr_i32 s1, s0, 31
	v_lshlrev_b32_e32 v154, 6, v160
	v_and_b32_e32 v163, 1, v151
	s_lshl_b64 s[6:7], s[0:1], 11
	s_lshl_b32 s13, s12, 7
	v_ashrrev_i32_e32 v155, 31, v154
	v_and_b32_e32 v162, 15, v153
	s_or_b32 s6, s6, s13
	v_lshlrev_b32_e32 v164, 6, v163
	v_lshl_add_u64 v[2:3], v[154:155], 1, s[48:49]
	v_and_b32_e32 v0, 48, v153
	v_lshl_add_u64 v[2:3], v[2:3], 0, v[0:1]
	v_or3_b32 v156, s6, v164, v162
	v_mad_u64_u32 v[20:21], s[8:9], v156, s87, v[2:3]
	v_mad_i32_i24 v21, s7, v215, v21
	v_or_b32_e32 v152, 16, v156
	v_or_b32_e32 v150, 32, v156
	v_or_b32_e32 v148, 48, v156
	global_load_dwordx4 v[64:67], v[20:21], off
	global_load_dwordx4 v[60:63], v[20:21], off offset:64
	v_mad_u64_u32 v[20:21], s[8:9], v152, s87, v[2:3]
	s_waitcnt vmcnt(2)
	v_readlane_b32 s98, v252, 44
	v_readlane_b32 s99, v252, 45
	v_add_u32_e32 v236, s93, v160
	v_ashrrev_i32_e32 v237, 31, v236
	v_lshl_add_u64 v[236:237], v[236:237], 2, s[98:99]
	global_load_dword v238, v[236:237], off
	v_mad_u64_u32 v[28:29], s[8:9], v150, s87, v[2:3]
	v_mad_u64_u32 v[2:3], s[8:9], v148, s87, v[2:3]
	v_mad_i32_i24 v21, s7, v215, v21
	v_mad_i32_i24 v29, s7, v215, v29
	v_mad_i32_i24 v3, s7, v215, v3
	global_load_dwordx4 v[24:27], v[20:21], off
	s_nop 0
	global_load_dwordx4 v[20:23], v[20:21], off offset:64
	s_nop 0
	global_load_dwordx4 v[52:55], v[28:29], off
	s_nop 0
	global_load_dwordx4 v[28:31], v[28:29], off offset:64
	s_nop 0
	global_load_dwordx4 v[56:59], v[2:3], off
	global_load_dwordx4 v[48:51], v[2:3], off offset:64
	v_lshlrev_b32_e32 v2, 7, v153
	v_and_b32_e32 v2, 0x80, v2
	global_load_dwordx4 v[100:103], v2, s[42:43] offset:48
	global_load_dwordx4 v[104:107], v2, s[42:43] offset:32
	global_load_dwordx4 v[108:111], v2, s[42:43] offset:16
	global_load_dwordx4 v[112:115], v2, s[42:43]
	global_load_dwordx4 v[84:87], v2, s[42:43] offset:112
	global_load_dwordx4 v[88:91], v2, s[42:43] offset:96
	global_load_dwordx4 v[92:95], v2, s[42:43] offset:80
	global_load_dwordx4 v[96:99], v2, s[42:43] offset:64
	v_bfe_u32 v165, v153, 4, 2
	v_lshlrev_b32_e32 v2, 5, v165
	global_load_dwordx4 v[40:43], v2, s[44:45] offset:16
	global_load_dwordx4 v[44:47], v2, s[44:45]
	global_load_dwordx4 v[32:35], v2, s[44:45] offset:144
	global_load_dwordx4 v[36:39], v2, s[44:45] offset:128
	v_ashrrev_i32_e32 v3, 1, v153
	v_add_u32_e32 v2, 0xffffff80, v3
	v_and_b32_e32 v149, 1, v153
	v_add_u32_e32 v117, s13, v2
	v_mov_b32_e32 v157, s7
	v_cmp_lt_i32_e32 vcc, -1, v117
	v_mov_b32_e32 v118, 0
	v_mov_b32_e32 v68, 0
	v_lshlrev_b32_e32 v116, 6, v149
	v_mov_b32_e32 v69, 0
	v_mov_b32_e32 v70, 0
	v_mov_b32_e32 v71, 0
	v_mov_b32_e32 v72, 0
	v_mov_b32_e32 v73, 0
	v_mov_b32_e32 v74, 0
	v_mov_b32_e32 v75, 0
	v_mov_b32_e32 v76, 0
	v_mov_b32_e32 v77, 0
	v_mov_b32_e32 v78, 0
	v_mov_b32_e32 v79, 0
	v_mov_b32_e32 v80, 0
	v_mov_b32_e32 v81, 0
	v_mov_b32_e32 v82, 0
	v_mov_b32_e32 v83, 0
	v_mov_b32_e32 v119, 0
	v_mov_b32_e32 v144, 0
	v_mov_b32_e32 v145, 0
	v_mov_b32_e32 v140, 0
	v_mov_b32_e32 v141, 0
	v_mov_b32_e32 v134, 0
	v_mov_b32_e32 v135, 0
	v_mov_b32_e32 v158, 0
	v_mov_b32_e32 v159, 0
	v_mov_b32_e32 v146, 0
	v_mov_b32_e32 v147, 0
	v_mov_b32_e32 v142, 0
	v_mov_b32_e32 v143, 0
	v_mov_b32_e32 v136, 0
	v_mov_b32_e32 v137, 0
	v_mov_b32_e32 v130, 0
	v_mov_b32_e32 v131, 0
	v_mov_b32_e32 v138, 0
	v_mov_b32_e32 v139, 0
	v_mov_b32_e32 v132, 0
	v_mov_b32_e32 v133, 0
	v_mov_b32_e32 v128, 0
	v_mov_b32_e32 v129, 0
	v_mov_b32_e32 v126, 0
	v_mov_b32_e32 v127, 0
	v_mov_b32_e32 v124, 0
	v_mov_b32_e32 v125, 0
	v_mov_b32_e32 v122, 0
	v_mov_b32_e32 v123, 0
	v_mov_b32_e32 v120, 0
	v_mov_b32_e32 v121, 0
	s_and_saveexec_b64 s[6:7], vcc
	s_cbranch_execz .LBB0_366
	v_lshl_add_u32 v70, s0, 11, v117
	v_mov_b64_e32 v[68:69], s[48:49]
	v_mad_i64_i32 v[68:69], s[8:9], v70, s87, v[68:69]
	s_lshl_b32 s26, s11, 7
	v_lshl_add_u64 v[68:69], v[68:69], 0, s[26:27]
	v_mov_b32_e32 v117, v1
	v_lshl_add_u64 v[80:81], v[68:69], 0, v[116:117]
	global_load_dwordx4 v[120:123], v[80:81], off offset:1024
	global_load_dwordx4 v[124:127], v[80:81], off offset:1040
	global_load_dwordx4 v[166:169], v[80:81], off offset:1056
	global_load_dwordx4 v[170:173], v[80:81], off offset:1072
	global_load_dwordx4 v[68:71], v[80:81], off offset:1328
	global_load_dwordx4 v[72:75], v[80:81], off offset:1312
	global_load_dwordx4 v[76:79], v[80:81], off offset:1296
	s_nop 0
	global_load_dwordx4 v[80:83], v[80:81], off offset:1280
	s_waitcnt vmcnt(7)
	v_lshlrev_b32_e32 v118, 16, v120
	v_and_b32_e32 v119, 0xffff0000, v120
	v_lshlrev_b32_e32 v144, 16, v121
	v_and_b32_e32 v145, 0xffff0000, v121
	v_lshlrev_b32_e32 v140, 16, v122
	v_and_b32_e32 v141, 0xffff0000, v122
	v_lshlrev_b32_e32 v134, 16, v123
	v_and_b32_e32 v135, 0xffff0000, v123
	s_waitcnt vmcnt(6)
	v_lshlrev_b32_e32 v158, 16, v124
	v_and_b32_e32 v159, 0xffff0000, v124
	v_lshlrev_b32_e32 v146, 16, v125
	v_and_b32_e32 v147, 0xffff0000, v125
	v_lshlrev_b32_e32 v142, 16, v126
	v_and_b32_e32 v143, 0xffff0000, v126
	v_lshlrev_b32_e32 v136, 16, v127
	v_and_b32_e32 v137, 0xffff0000, v127
	s_waitcnt vmcnt(5)
	v_lshlrev_b32_e32 v130, 16, v166
	v_and_b32_e32 v131, 0xffff0000, v166
	v_lshlrev_b32_e32 v138, 16, v167
	v_and_b32_e32 v139, 0xffff0000, v167
	v_lshlrev_b32_e32 v132, 16, v168
	v_and_b32_e32 v133, 0xffff0000, v168
	v_lshlrev_b32_e32 v128, 16, v169
	v_and_b32_e32 v129, 0xffff0000, v169
	s_waitcnt vmcnt(4)
	v_lshlrev_b32_e32 v126, 16, v170
	v_and_b32_e32 v127, 0xffff0000, v170
	v_lshlrev_b32_e32 v124, 16, v171
	v_and_b32_e32 v125, 0xffff0000, v171
	v_lshlrev_b32_e32 v122, 16, v172
	v_and_b32_e32 v123, 0xffff0000, v172
	v_lshlrev_b32_e32 v120, 16, v173
	v_and_b32_e32 v121, 0xffff0000, v173

; __device__ __forceinline__ void unpack8(const u32x4 w, float (&f)[8]) { f[0] = bflo(w.x); f[1] = bfhi(w.x); f[2] = bflo(w.y); f[3] = bfhi(w.y); f[4] = bflo(w.z); f[5] = bfhi(w.z); f[6] = bflo(w.w); f[7] = bfhi(w.w); }
; __device__ __forceinline__ void attn_prompt_unit(const Args& a, LAS unsigned char* lds, int l, int b, int qb, int kvh, int tid) {
;     ...
;     float kmax = kmaxs[0];
; #pragma unroll
;     for (int w = 1; w < 8; ++w) kmax = fmaxf(kmax, kmaxs[w]);
;     const float cs = 0.125f * LOG2E, sinkl = a.in[I_SINK][l * 8 + h] * LOG2E, slope = exp2f(-(float)(h + 1)) * LOG2E;
;     bf16x8 qf[4][2]; float mref[4];
; #pragma unroll
;     for (int qt = 0; qt < 4; ++qt) {
;         float x[16]; { float t8[8]; unpack8(qraw[qt][0], t8);
; #pragma unroll
;             for (int k = 0; k < 8; ++k) x[k] = t8[k];
;             unpack8(qraw[qt][1], t8);
; #pragma unroll
;             for (int k = 0; k < 8; ++k) x[8 + k] = t8[k]; }
;         float sq = 0.f;
; #pragma unroll
;         for (int k = 0; k < 16; ++k) sq += x[k] * x[k];
;         sq += __shfl_xor(sq, 16); sq += __shfl_xor(sq, 32);
;         const float rs = rsqrtf(sq * (1.f / 64.f) + EPS); float n2 = 0.f;
; #pragma unroll
;         for (int k = 0; k < 16; ++k) { x[k] = x[k] * rs * gqv[k >> 2][k & 3]; n2 += x[k] * x[k]; }
;         n2 += __shfl_xor(n2, 16); n2 += __shfl_xor(n2, 32);
;         mref[qt] = fmaxf(sinkl, sqrtf(n2) * kmax * cs);
.LBB0_370:
	s_or_b64 exec, exec, s[6:7]
	s_nop 0
	v_add_u32_e32 v68, s93, v160
	v_readlane_b32 s52, v252, 38
	v_ashrrev_i32_e32 v69, 31, v68
	v_readlane_b32 s58, v252, 44
	v_readlane_b32 s59, v252, 45
	s_waitcnt lgkmcnt(0)
	s_barrier
	v_lshl_add_u64 v[68:69], v[68:69], 2, s[58:59]
	v_mov_b32_e32 v3, v238
	v_and_b32_e32 v77, 0xffff0000, v64
	v_lshlrev_b32_e32 v76, 16, v64
	v_lshlrev_b32_e32 v80, 16, v66
	v_and_b32_e32 v81, 0xffff0000, v66
	v_mul_f32_e32 v66, v77, v77
	v_lshlrev_b32_e32 v78, 16, v65
	v_fmac_f32_e32 v66, v76, v76
	v_and_b32_e32 v79, 0xffff0000, v65
	v_fmac_f32_e32 v66, v78, v78
	v_fmac_f32_e32 v66, v79, v79
	v_fmac_f32_e32 v66, v80, v80
	v_lshlrev_b32_e32 v82, 16, v67
	v_fmac_f32_e32 v66, v81, v81
	v_and_b32_e32 v83, 0xffff0000, v67
	v_fmac_f32_e32 v66, v82, v82
	v_and_b32_e32 v68, 0xffff0000, v60
	v_lshlrev_b32_e32 v69, 16, v60
	v_fmac_f32_e32 v66, v83, v83
	v_pk_mul_f32 v[64:65], v[68:69], v[68:69]
	v_and_b32_e32 v70, 0xffff0000, v61
	v_add_f32_e32 v60, v65, v66
	v_lshlrev_b32_e32 v71, 16, v61
	v_add_f32_e32 v64, v64, v60
	v_pk_mul_f32 v[60:61], v[70:71], v[70:71]
	v_and_b32_e32 v72, 0xffff0000, v62
	v_add_f32_e32 v61, v61, v64
	v_lshlrev_b32_e32 v73, 16, v62
	v_add_f32_e32 v64, v60, v61
	v_pk_mul_f32 v[60:61], v[72:73], v[72:73]
	v_and_b32_e32 v74, 0xffff0000, v63
	v_add_f32_e32 v61, v61, v64
	v_lshlrev_b32_e32 v75, 16, v63
	v_add_f32_e32 v62, v60, v61
	v_pk_mul_f32 v[60:61], v[74:75], v[74:75]
	s_add_i32 s0, 0, 0x11800
	v_add_f32_e32 v61, v61, v62
	v_add_f32_e32 v64, v60, v61
	ds_bpermute_b32 v65, v158, v64
	v_mov_b32_e32 v60, s0
	ds_read_b128 v[60:63], v60
	v_readlane_b32 s0, v255, 21
	v_and_b32_e32 v86, 0xffff0000, v26
	s_waitcnt lgkmcnt(1)
	v_add_f32_e32 v84, v64, v65
	ds_bpermute_b32 v85, v159, v84
	v_mov_b32_e32 v64, s0
	ds_read_b128 v[64:67], v64
	s_waitcnt lgkmcnt(2)
	v_max_f32_e32 v61, v61, v61
	v_max_f32_e32 v60, v60, v60
	s_waitcnt lgkmcnt(1)
	v_add_f32_e32 v84, v84, v85
	v_fmamk_f32 v84, v84, 0x3c800000, v185
	v_mul_f32_e32 v85, 0x4b800000, v84
	v_cmp_gt_f32_e32 vcc, s86, v84
	v_max_f32_e32 v60, v60, v61
	v_max3_f32 v60, v60, v62, v63
	v_cndmask_b32_e32 v84, v84, v85, vcc
	v_rsq_f32_e32 v84, v84
	s_waitcnt lgkmcnt(0)
	v_max3_f32 v60, v60, v64, v65
	v_max3_f32 v60, v60, v66, v67
	v_add_u32_e32 v66, 1, v160
	v_mul_f32_e32 v61, 0x45800000, v84
	v_cndmask_b32_e32 v61, v84, v61, vcc
	v_mul_f32_e32 v63, v61, v77
	v_mul_f32_e32 v62, v61, v76
	v_mul_f32_e32 v63, v45, v63
	v_mul_f32_e32 v62, v44, v62
	v_mul_f32_e32 v64, v63, v63
	v_mul_f32_e32 v65, v61, v78
	v_fmac_f32_e32 v64, v62, v62
	v_mul_f32_e32 v76, v46, v65
	v_mul_f32_e32 v65, v61, v79
	v_fmac_f32_e32 v64, v76, v76
	v_mul_f32_e32 v77, v47, v65
	v_mul_f32_e32 v65, v61, v80
	v_fmac_f32_e32 v64, v77, v77
	v_mul_f32_e32 v78, v40, v65
	v_mul_f32_e32 v65, v61, v81
	v_fmac_f32_e32 v64, v78, v78
	v_mul_f32_e32 v79, v41, v65
	v_mul_f32_e32 v65, v61, v82
	v_fmac_f32_e32 v64, v79, v79
	v_mul_f32_e32 v80, v42, v65
	v_mul_f32_e32 v65, v61, v83
	v_fmac_f32_e32 v64, v80, v80
	v_mul_f32_e32 v81, v43, v65
	v_mul_f32_e32 v65, v61, v69
	v_fmac_f32_e32 v64, v81, v81
	v_mul_f32_e32 v69, v36, v65
	v_mul_f32_e32 v65, v61, v68
	v_fmac_f32_e32 v64, v69, v69
	v_mul_f32_e32 v68, v37, v65
	v_mul_f32_e32 v65, v61, v71
	v_fmac_f32_e32 v64, v68, v68
	v_mul_f32_e32 v71, v38, v65
	v_mul_f32_e32 v65, v61, v70
	v_fmac_f32_e32 v64, v71, v71
	v_mul_f32_e32 v70, v39, v65
	v_mul_f32_e32 v65, v61, v73
	v_fmac_f32_e32 v64, v70, v70
	v_mul_f32_e32 v73, v32, v65
	v_mul_f32_e32 v65, v61, v72
	v_fmac_f32_e32 v64, v73, v73
	v_mul_f32_e32 v72, v33, v65
	v_mul_f32_e32 v65, v61, v75
	v_fmac_f32_e32 v64, v72, v72
	v_mul_f32_e32 v75, v34, v65
	v_mul_f32_e32 v61, v61, v74
	v_fmac_f32_e32 v64, v75, v75
	v_mul_f32_e32 v61, v35, v61
	v_fmac_f32_e32 v64, v61, v61
	ds_bpermute_b32 v65, v158, v64
	s_nop 0
	v_mul_f32_e32 v160, 0x3fb8aa3b, v3
	v_cvt_f32_i32_e32 v66, v66
	s_mov_b32 s0, 0x42fc0000
	v_and_b32_e32 v82, 0xffff0000, v24
	s_waitcnt lgkmcnt(0)
	v_add_f32_e32 v3, v64, v65
	ds_bpermute_b32 v64, v159, v3
	v_cmp_lt_f32_e32 vcc, s0, v66
	v_mov_b32_e32 v65, 0x42800000
	s_mov_b32 s0, 0xf800000
	v_cndmask_b32_e32 v65, 0, v65, vcc
	s_waitcnt lgkmcnt(0)
	v_add_f32_e32 v3, v3, v64
	v_mul_f32_e32 v64, 0x4f800000, v3
	v_cmp_gt_f32_e64 s[6:7], s0, v3
	v_sub_f32_e32 v65, v65, v66
	v_exp_f32_e32 v65, v65
	v_cndmask_b32_e64 v64, v3, v64, s[6:7]
	v_sqrt_f32_e32 v66, v64
	v_not_b32_e32 v3, 63
	v_cndmask_b32_e32 v3, 0, v3, vcc
	v_ldexp_f32 v3, v65, v3
	v_add_u32_e32 v65, -1, v66
	v_fma_f32 v67, -v65, v66, v64
	v_cmp_ge_f32_e32 vcc, 0, v67
	v_add_u32_e32 v67, 1, v66
	v_lshlrev_b32_e32 v74, 16, v24
	v_cndmask_b32_e32 v65, v66, v65, vcc
	v_fma_f32 v66, -v67, v66, v64
	v_cmp_lt_f32_e32 vcc, 0, v66
	v_lshlrev_b32_e32 v83, 16, v25
	v_and_b32_e32 v84, 0xffff0000, v25
	v_cndmask_b32_e32 v65, v65, v67, vcc
	v_mul_f32_e32 v66, 0x37800000, v65
	v_cndmask_b32_e64 v65, v65, v66, s[6:7]
	v_mul_f32_e32 v66, 0x3e38aa3b, v62
	v_mul_f32_e32 v62, v82, v82
	v_fmac_f32_e32 v62, v74, v74
	v_fmac_f32_e32 v62, v83, v83
	v_lshlrev_b32_e32 v85, 16, v26
	v_fmac_f32_e32 v62, v84, v84
	v_fmac_f32_e32 v62, v85, v85
	v_lshlrev_b32_e32 v87, 16, v27
	v_fmac_f32_e32 v62, v86, v86
	v_and_b32_e32 v88, 0xffff0000, v27
	v_fmac_f32_e32 v62, v87, v87
	v_and_b32_e32 v24, 0xffff0000, v20
	v_lshlrev_b32_e32 v25, 16, v20
	v_mov_b32_e32 v91, 0x260
	v_fmac_f32_e32 v62, v88, v88
	v_pk_mul_f32 v[26:27], v[24:25], v[24:25]
	v_cmp_class_f32_e32 vcc, v64, v91
	v_add_f32_e32 v20, v27, v62
	v_add_f32_e32 v62, v26, v20
	v_cndmask_b32_e32 v64, v65, v64, vcc
	v_and_b32_e32 v26, 0xffff0000, v21
	v_lshlrev_b32_e32 v27, 16, v21
	v_mul_f32_e32 v64, v60, v64
	v_pk_mul_f32 v[20:21], v[26:27], v[26:27]
	v_mul_f32_e32 v64, 0x3e38aa3b, v64
	v_mul_f32_e32 v67, 0x3e38aa3b, v63
	v_add_f32_e32 v21, v21, v62
	v_and_b32_e32 v62, 0xffff0000, v22
	v_lshlrev_b32_e32 v63, 16, v22
	v_max_f32_e32 v161, v160, v64
	v_add_f32_e32 v64, v20, v21
	v_pk_mul_f32 v[20:21], v[62:63], v[62:63]
	v_lshlrev_b32_e32 v65, 16, v23
	v_add_f32_e32 v21, v21, v64
	v_and_b32_e32 v64, 0xffff0000, v23
	v_add_f32_e32 v22, v20, v21
	v_pk_mul_f32 v[20:21], v[64:65], v[64:65]
	v_mul_f32_e32 v61, 0x3e38aa3b, v61
	v_add_f32_e32 v21, v21, v22
	v_add_f32_e32 v22, v20, v21
	ds_bpermute_b32 v23, v158, v22
	v_cvt_pk_bf16_f32 v20, v66, v67
	v_mul_f32_e32 v21, 0x3e38aa3b, v76
	v_mul_f32_e32 v66, 0x3e38aa3b, v77
	v_cvt_pk_bf16_f32 v21, v21, v66
	s_waitcnt lgkmcnt(0)
; __device__ __forceinline__ unsigned pk2(float lo, float hi) { return pg8::cvt_pk_bf16(lo, hi); }
; __device__ __forceinline__ void unpack8(const u32x4 w, float (&f)[8]) { f[0] = bflo(w.x); f[1] = bfhi(w.x); f[2] = bflo(w.y); f[3] = bfhi(w.y); f[4] = bflo(w.z); f[5] = bfhi(w.z); f[6] = bflo(w.w); f[7] = bfhi(w.w); }
; __device__ __forceinline__ void attn_prompt_unit(const Args& a, LAS unsigned char* lds, int l, int b, int qb, int kvh, int tid) {
;     ...
;     for (int qt = 0; qt < 4; ++qt) {
;         float x[16]; { float t8[8]; unpack8(qraw[qt][0], t8);
; #pragma unroll
;             for (int k = 0; k < 8; ++k) x[k] = t8[k];
;             unpack8(qraw[qt][1], t8);
; #pragma unroll
;             for (int k = 0; k < 8; ++k) x[8 + k] = t8[k]; }
;         float sq = 0.f;
; #pragma unroll
;         for (int k = 0; k < 16; ++k) sq += x[k] * x[k];
;         sq += __shfl_xor(sq, 16); sq += __shfl_xor(sq, 32);
;         const float rs = rsqrtf(sq * (1.f / 64.f) + EPS); float n2 = 0.f;
; #pragma unroll
;         for (int k = 0; k < 16; ++k) { x[k] = x[k] * rs * gqv[k >> 2][k & 3]; n2 += x[k] * x[k]; }
;         n2 += __shfl_xor(n2, 16); n2 += __shfl_xor(n2, 32);
;         mref[qt] = fmaxf(sinkl, sqrtf(n2) * kmax * cs);
; #pragma unroll
;         for (int s = 0; s < 2; ++s) { u32x4 w; w.x = pk2(x[8 * s] * cs, x[8 * s + 1] * cs); w.y = pk2(x[8 * s + 2] * cs, x[8 * s + 3] * cs); w.z = pk2(x[8 * s + 4] * cs, x[8 * s + 5] * cs); w.w = pk2(x[8 * s + 6] * cs, x[8 * s + 7] * cs);
;             qf[qt][s] = __builtin_bit_cast(bf16x8, w); }
	v_add_f32_e32 v23, v22, v23
	ds_bpermute_b32 v66, v159, v23
	v_mul_f32_e32 v22, 0x3e38aa3b, v78
	v_mul_f32_e32 v67, 0x3e38aa3b, v79
	v_cvt_pk_bf16_f32 v22, v22, v67
	v_mul_f32_e32 v67, 0x3e38aa3b, v80
	s_waitcnt lgkmcnt(0)
	v_add_f32_e32 v23, v23, v66
	v_fmamk_f32 v23, v23, 0x3c800000, v185
	v_mul_f32_e32 v66, 0x4b800000, v23
	v_cmp_gt_f32_e32 vcc, s86, v23
	v_mul_f32_e32 v170, 0x3fb8aa3b, v3
	s_cmp_eq_u32 s12, 0
	v_cndmask_b32_e32 v23, v23, v66, vcc
	v_rsq_f32_e32 v66, v23
	v_mul_f32_e32 v23, 0x3e38aa3b, v81
	v_cvt_pk_bf16_f32 v23, v67, v23
	v_mul_f32_e32 v67, 0x3e38aa3b, v69
	v_mul_f32_e32 v69, 0x45800000, v66
	v_cndmask_b32_e32 v66, v66, v69, vcc
	v_mul_f32_e32 v69, v66, v74
	v_mul_f32_e32 v74, v66, v82
	v_mul_f32_e32 v74, v45, v74
	v_mul_f32_e32 v69, v44, v69
	v_mul_f32_e32 v76, v74, v74
	v_mul_f32_e32 v77, v66, v83
	v_fmac_f32_e32 v76, v69, v69
	v_mul_f32_e32 v77, v46, v77
	v_mul_f32_e32 v78, v66, v84
	v_fmac_f32_e32 v76, v77, v77
	v_mul_f32_e32 v78, v47, v78
	v_mul_f32_e32 v79, v66, v85
	v_fmac_f32_e32 v76, v78, v78
	v_mul_f32_e32 v79, v40, v79
	v_mul_f32_e32 v80, v66, v86
	v_fmac_f32_e32 v76, v79, v79
	v_mul_f32_e32 v80, v41, v80
	v_mul_f32_e32 v81, v66, v87
	v_fmac_f32_e32 v76, v80, v80
	v_mul_f32_e32 v81, v42, v81
	v_mul_f32_e32 v82, v66, v88
	v_fmac_f32_e32 v76, v81, v81
	v_mul_f32_e32 v82, v43, v82
	v_mul_f32_e32 v25, v66, v25
	v_fmac_f32_e32 v76, v82, v82
	v_mul_f32_e32 v83, v36, v25
	v_mul_f32_e32 v24, v66, v24
	v_fmac_f32_e32 v76, v83, v83
	v_mul_f32_e32 v84, v37, v24
	v_mul_f32_e32 v24, v66, v27
	v_fmac_f32_e32 v76, v84, v84
	v_mul_f32_e32 v85, v38, v24
	v_mul_f32_e32 v24, v66, v26
	v_fmac_f32_e32 v76, v85, v85
	v_mul_f32_e32 v86, v39, v24
	v_mul_f32_e32 v24, v66, v63
	v_fmac_f32_e32 v76, v86, v86
	v_mul_f32_e32 v87, v32, v24
	v_mul_f32_e32 v24, v66, v62
	v_fmac_f32_e32 v76, v87, v87
	v_mul_f32_e32 v88, v33, v24
	v_mul_f32_e32 v24, v66, v65
	v_fmac_f32_e32 v76, v88, v88
	v_mul_f32_e32 v89, v34, v24
	v_mul_f32_e32 v24, v66, v64
	v_fmac_f32_e32 v76, v89, v89
	v_mul_f32_e32 v66, v35, v24
	v_fmac_f32_e32 v76, v66, v66
	ds_bpermute_b32 v25, v158, v76
	v_mul_f32_e32 v24, 0x3e38aa3b, v68
	v_mul_f32_e32 v26, 0x3e38aa3b, v71
	v_mul_f32_e32 v27, 0x3e38aa3b, v70
	v_cvt_pk_bf16_f32 v24, v67, v24
	s_waitcnt lgkmcnt(0)
	v_add_f32_e32 v62, v76, v25
	ds_bpermute_b32 v63, v159, v62
	v_cvt_pk_bf16_f32 v25, v26, v27
	v_mul_f32_e32 v26, 0x3e38aa3b, v73
	v_mul_f32_e32 v27, 0x3e38aa3b, v72
	v_cvt_pk_bf16_f32 v26, v26, v27
	s_waitcnt lgkmcnt(0)
	v_add_f32_e32 v27, v62, v63
	v_mul_f32_e32 v62, 0x4f800000, v27
	v_cmp_gt_f32_e32 vcc, s0, v27
	v_lshlrev_b32_e32 v68, 16, v52
	v_lshlrev_b32_e32 v70, 16, v53
	v_cndmask_b32_e32 v62, v27, v62, vcc
	v_sqrt_f32_e32 v63, v62
	v_mul_f32_e32 v27, 0x3e38aa3b, v75
	v_cvt_pk_bf16_f32 v27, v27, v61
	v_and_b32_e32 v71, 0xffff0000, v53
	v_add_u32_e32 v61, -1, v63
	v_fma_f32 v64, -v61, v63, v62
	v_cmp_ge_f32_e64 s[6:7], 0, v64
	v_add_u32_e32 v64, 1, v63
	v_lshlrev_b32_e32 v72, 16, v54
	v_cndmask_b32_e64 v61, v63, v61, s[6:7]
	v_fma_f32 v63, -v64, v63, v62
	v_cmp_lt_f32_e64 s[6:7], 0, v63
	v_and_b32_e32 v73, 0xffff0000, v54
	v_mul_f32_e32 v67, 0x3e38aa3b, v74
	v_cndmask_b32_e64 v61, v61, v64, s[6:7]
	v_mul_f32_e32 v63, 0x37800000, v61
	v_cndmask_b32_e32 v61, v61, v63, vcc
	v_cmp_class_f32_e32 vcc, v62, v91
	v_lshlrev_b32_e32 v74, 16, v55
	v_and_b32_e32 v75, 0xffff0000, v55
	v_cndmask_b32_e32 v61, v61, v62, vcc
	v_mul_f32_e32 v61, v60, v61
	v_mul_f32_e32 v61, 0x3e38aa3b, v61
	v_max_f32_e32 v166, v160, v61
	v_mul_f32_e32 v61, 0x3e38aa3b, v69
	v_and_b32_e32 v69, 0xffff0000, v52
	v_mul_f32_e32 v62, v69, v69
	v_fmac_f32_e32 v62, v68, v68
	v_fmac_f32_e32 v62, v70, v70
	v_fmac_f32_e32 v62, v71, v71
	v_fmac_f32_e32 v62, v72, v72
	v_fmac_f32_e32 v62, v73, v73
	v_fmac_f32_e32 v62, v74, v74
	v_and_b32_e32 v52, 0xffff0000, v28
	v_lshlrev_b32_e32 v53, 16, v28
	v_fmac_f32_e32 v62, v75, v75
	v_pk_mul_f32 v[54:55], v[52:53], v[52:53]
	v_lshlrev_b32_e32 v63, 16, v30
	v_add_f32_e32 v28, v55, v62
	v_add_f32_e32 v62, v54, v28
	v_and_b32_e32 v54, 0xffff0000, v29
	v_lshlrev_b32_e32 v55, 16, v29
	v_pk_mul_f32 v[28:29], v[54:55], v[54:55]
	v_lshlrev_b32_e32 v65, 16, v31
	v_add_f32_e32 v29, v29, v62
	v_and_b32_e32 v62, 0xffff0000, v30
	v_add_f32_e32 v64, v28, v29
	v_pk_mul_f32 v[28:29], v[62:63], v[62:63]
	v_lshlrev_b32_e32 v3, 1, v163
	v_add_f32_e32 v29, v29, v64
	v_and_b32_e32 v64, 0xffff0000, v31
	v_add_f32_e32 v30, v28, v29
	v_pk_mul_f32 v[28:29], v[64:65], v[64:65]
	v_sub_u32_e32 v3, 4, v3
	v_add_f32_e32 v29, v29, v30
	v_add_f32_e32 v30, v28, v29
	ds_bpermute_b32 v31, v158, v30
	v_cvt_pk_bf16_f32 v28, v61, v67
	v_mul_f32_e32 v29, 0x3e38aa3b, v77
	v_mul_f32_e32 v61, 0x3e38aa3b, v78
	v_cvt_pk_bf16_f32 v29, v29, v61
	s_waitcnt lgkmcnt(0)
	v_add_f32_e32 v31, v30, v31
	ds_bpermute_b32 v61, v159, v31
	v_mul_f32_e32 v30, 0x3e38aa3b, v79
	v_mul_f32_e32 v67, 0x3e38aa3b, v80
	v_cvt_pk_bf16_f32 v30, v30, v67
	v_mul_f32_e32 v67, 0x3e38aa3b, v81
	s_waitcnt lgkmcnt(0)
; __device__ __forceinline__ unsigned pk2(float lo, float hi) { return pg8::cvt_pk_bf16(lo, hi); }
; __device__ __forceinline__ void unpack8(const u32x4 w, float (&f)[8]) { f[0] = bflo(w.x); f[1] = bfhi(w.x); f[2] = bflo(w.y); f[3] = bfhi(w.y); f[4] = bflo(w.z); f[5] = bfhi(w.z); f[6] = bflo(w.w); f[7] = bfhi(w.w); }
; __device__ __forceinline__ void attn_prompt_unit(const Args& a, LAS unsigned char* lds, int l, int b, int qb, int kvh, int tid) {
;     ...
;     for (int qt = 0; qt < 4; ++qt) {
;         float x[16]; { float t8[8]; unpack8(qraw[qt][0], t8);
; #pragma unroll
;             for (int k = 0; k < 8; ++k) x[k] = t8[k];
;             unpack8(qraw[qt][1], t8);
; #pragma unroll
;             for (int k = 0; k < 8; ++k) x[8 + k] = t8[k]; }
;         float sq = 0.f;
; #pragma unroll
;         for (int k = 0; k < 16; ++k) sq += x[k] * x[k];
;         sq += __shfl_xor(sq, 16); sq += __shfl_xor(sq, 32);
;         const float rs = rsqrtf(sq * (1.f / 64.f) + EPS); float n2 = 0.f;
; #pragma unroll
;         for (int k = 0; k < 16; ++k) { x[k] = x[k] * rs * gqv[k >> 2][k & 3]; n2 += x[k] * x[k]; }
;         n2 += __shfl_xor(n2, 16); n2 += __shfl_xor(n2, 32);
;         mref[qt] = fmaxf(sinkl, sqrtf(n2) * kmax * cs);
; #pragma unroll
;         for (int s = 0; s < 2; ++s) { u32x4 w; w.x = pk2(x[8 * s] * cs, x[8 * s + 1] * cs); w.y = pk2(x[8 * s + 2] * cs, x[8 * s + 3] * cs); w.z = pk2(x[8 * s + 4] * cs, x[8 * s + 5] * cs); w.w = pk2(x[8 * s + 6] * cs, x[8 * s + 7] * cs);
;             qf[qt][s] = __builtin_bit_cast(bf16x8, w); }
	v_add_f32_e32 v31, v31, v61
	v_fmamk_f32 v31, v31, 0x3c800000, v185
	v_mul_f32_e32 v61, 0x4b800000, v31
	v_cmp_gt_f32_e32 vcc, s86, v31
	v_and_b32_e32 v80, 0xffff0000, v57
	v_lshlrev_b32_e32 v2, 3, v165
	v_cndmask_b32_e32 v31, v31, v61, vcc
	v_rsq_f32_e32 v61, v31
	v_mul_f32_e32 v31, 0x3e38aa3b, v82
	v_cvt_pk_bf16_f32 v31, v67, v31
	v_mul_f32_e32 v67, 0x3e38aa3b, v83
	v_mul_f32_e32 v76, 0x45800000, v61
	v_cndmask_b32_e32 v61, v61, v76, vcc
	v_mul_f32_e32 v69, v61, v69
	v_mul_f32_e32 v68, v61, v68
	v_mul_f32_e32 v69, v45, v69
	v_mul_f32_e32 v68, v44, v68
	v_mul_f32_e32 v76, v69, v69
	v_mul_f32_e32 v70, v61, v70
	v_fmac_f32_e32 v76, v68, v68
	v_mul_f32_e32 v70, v46, v70
	v_mul_f32_e32 v71, v61, v71
	v_fmac_f32_e32 v76, v70, v70
	v_mul_f32_e32 v71, v47, v71
	v_mul_f32_e32 v72, v61, v72
	v_fmac_f32_e32 v76, v71, v71
	v_mul_f32_e32 v72, v40, v72
	v_mul_f32_e32 v73, v61, v73
	v_fmac_f32_e32 v76, v72, v72
	v_mul_f32_e32 v73, v41, v73
	v_mul_f32_e32 v74, v61, v74
	v_fmac_f32_e32 v76, v73, v73
	v_mul_f32_e32 v74, v42, v74
	v_mul_f32_e32 v75, v61, v75
	v_fmac_f32_e32 v76, v74, v74
	v_mul_f32_e32 v75, v43, v75
	v_mul_f32_e32 v53, v61, v53
	v_fmac_f32_e32 v76, v75, v75
	v_mul_f32_e32 v77, v36, v53
	v_mul_f32_e32 v52, v61, v52
	v_fmac_f32_e32 v76, v77, v77
	v_mul_f32_e32 v78, v37, v52
	v_mul_f32_e32 v52, v61, v55
	v_fmac_f32_e32 v76, v78, v78
	v_mul_f32_e32 v79, v38, v52
	v_mul_f32_e32 v52, v61, v54
	v_fmac_f32_e32 v76, v79, v79
	v_mul_f32_e32 v81, v39, v52
	v_mul_f32_e32 v52, v61, v63
	v_fmac_f32_e32 v76, v81, v81
	v_mul_f32_e32 v82, v32, v52
	v_mul_f32_e32 v52, v61, v62
	v_fmac_f32_e32 v76, v82, v82
	v_mul_f32_e32 v83, v33, v52
	v_mul_f32_e32 v52, v61, v65
	v_fmac_f32_e32 v76, v83, v83
	v_mul_f32_e32 v90, v34, v52
	v_mul_f32_e32 v52, v61, v64
	v_fmac_f32_e32 v76, v90, v90
	v_mul_f32_e32 v61, v35, v52
	v_fmac_f32_e32 v76, v61, v61
	ds_bpermute_b32 v53, v158, v76
	v_mul_f32_e32 v52, 0x3e38aa3b, v84
	v_mul_f32_e32 v54, 0x3e38aa3b, v85
	v_mul_f32_e32 v55, 0x3e38aa3b, v86
	v_cvt_pk_bf16_f32 v52, v67, v52
	s_waitcnt lgkmcnt(0)
	v_add_f32_e32 v62, v76, v53
	ds_bpermute_b32 v63, v159, v62
	v_cvt_pk_bf16_f32 v53, v54, v55
	v_mul_f32_e32 v54, 0x3e38aa3b, v87
	v_mul_f32_e32 v55, 0x3e38aa3b, v88
	v_cvt_pk_bf16_f32 v54, v54, v55
	s_waitcnt lgkmcnt(0)
	v_add_f32_e32 v55, v62, v63
	v_mul_f32_e32 v62, 0x4f800000, v55
	v_cmp_gt_f32_e32 vcc, s0, v55
	v_mul_f32_e32 v64, 0x3e38aa3b, v66
	v_mul_f32_e32 v67, 0x3e38aa3b, v69
	v_cndmask_b32_e32 v62, v55, v62, vcc
	v_sqrt_f32_e32 v63, v62
	v_mul_f32_e32 v55, 0x3e38aa3b, v89
	v_cvt_pk_bf16_f32 v55, v55, v64
	v_and_b32_e32 v69, 0xffff0000, v56
	v_add_u32_e32 v64, -1, v63
	v_fma_f32 v65, -v64, v63, v62
	v_cmp_ge_f32_e64 s[6:7], 0, v65
	v_add_u32_e32 v65, 1, v63
	v_mul_f32_e32 v66, 0x3e38aa3b, v68
	v_cndmask_b32_e64 v64, v63, v64, s[6:7]
	v_fma_f32 v63, -v65, v63, v62
	v_cmp_lt_f32_e64 s[6:7], 0, v63
	v_lshlrev_b32_e32 v68, 16, v56
	v_lshlrev_b32_e32 v84, 16, v58
	v_cndmask_b32_e64 v63, v64, v65, s[6:7]
	v_and_b32_e32 v85, 0xffff0000, v58
	v_mul_f32_e32 v58, v69, v69
	v_mul_f32_e32 v64, 0x37800000, v63
	v_lshlrev_b32_e32 v76, 16, v57
	v_fmac_f32_e32 v58, v68, v68
	v_cndmask_b32_e32 v63, v63, v64, vcc
	v_cmp_class_f32_e32 vcc, v62, v91
	v_fmac_f32_e32 v58, v76, v76
	v_fmac_f32_e32 v58, v80, v80
	v_cndmask_b32_e32 v62, v63, v62, vcc
	v_mul_f32_e32 v62, v60, v62
	v_fmac_f32_e32 v58, v84, v84
	v_mul_f32_e32 v62, 0x3e38aa3b, v62
	v_lshlrev_b32_e32 v86, 16, v59
	v_fmac_f32_e32 v58, v85, v85
	v_max_f32_e32 v167, v160, v62
	v_and_b32_e32 v87, 0xffff0000, v59
	v_fmac_f32_e32 v58, v86, v86
	v_and_b32_e32 v62, 0xffff0000, v48
	v_lshlrev_b32_e32 v63, 16, v48
	v_fmac_f32_e32 v58, v87, v87
	v_pk_mul_f32 v[56:57], v[62:63], v[62:63]
	v_and_b32_e32 v64, 0xffff0000, v50
	v_add_f32_e32 v48, v57, v58
	v_add_f32_e32 v58, v56, v48
	v_and_b32_e32 v48, 0xffff0000, v49
	v_lshlrev_b32_e32 v49, 16, v49
	v_pk_mul_f32 v[56:57], v[48:49], v[48:49]
	v_lshlrev_b32_e32 v65, 16, v50
	v_add_f32_e32 v57, v57, v58
	v_add_f32_e32 v58, v56, v57
	v_pk_mul_f32 v[56:57], v[64:65], v[64:65]
	v_lshlrev_b32_e32 v165, 2, v165
	v_add_f32_e32 v50, v57, v58
	v_add_f32_e32 v58, v56, v50
	v_and_b32_e32 v50, 0xffff0000, v51
	v_lshlrev_b32_e32 v51, 16, v51
	v_pk_mul_f32 v[56:57], v[50:51], v[50:51]
	v_mov_b32_e32 v153, v157
	v_add_f32_e32 v57, v57, v58
	v_add_f32_e32 v58, v56, v57
	ds_bpermute_b32 v59, v158, v58
	v_cvt_pk_bf16_f32 v56, v66, v67
	v_mul_f32_e32 v57, 0x3e38aa3b, v70
	v_mul_f32_e32 v66, 0x3e38aa3b, v71
	v_cvt_pk_bf16_f32 v57, v57, v66
	s_waitcnt lgkmcnt(0)
	v_add_f32_e32 v59, v58, v59
	ds_bpermute_b32 v66, v159, v59
	v_mul_f32_e32 v58, 0x3e38aa3b, v72
	v_mul_f32_e32 v67, 0x3e38aa3b, v73
	v_cvt_pk_bf16_f32 v58, v58, v67
	v_mul_f32_e32 v67, 0x3e38aa3b, v74
	s_waitcnt lgkmcnt(0)
; __device__ __forceinline__ unsigned pk2(float lo, float hi) { return pg8::cvt_pk_bf16(lo, hi); }
; __device__ __forceinline__ void attn_prompt_unit(const Args& a, LAS unsigned char* lds, int l, int b, int qb, int kvh, int tid) {
;     ...
;         mref[qt] = fmaxf(sinkl, sqrtf(n2) * kmax * cs);
; #pragma unroll
;         for (int s = 0; s < 2; ++s) { u32x4 w; w.x = pk2(x[8 * s] * cs, x[8 * s + 1] * cs); w.y = pk2(x[8 * s + 2] * cs, x[8 * s + 3] * cs); w.z = pk2(x[8 * s + 4] * cs, x[8 * s + 5] * cs); w.w = pk2(x[8 * s + 6] * cs, x[8 * s + 7] * cs);
;             qf[qt][s] = __builtin_bit_cast(bf16x8, w); }
;     }
;     f32x4 O[4][4]; float lsum[4];
; #pragma unroll
;     for (int qt = 0; qt < 4; ++qt) { lsum[qt] = 0.f;
; #pragma unroll
;         for (int dt = 0; dt < 4; ++dt) O[qt][dt] = (f32x4){0.f, 0.f, 0.f, 0.f}; }
;     const int base = r - 4 * qd;
; #pragma unroll
;     for (int qt = 0; qt < 4; ++qt) mref[qt] += slope * (float)base;
	v_add_f32_e32 v59, v59, v66
	v_fmamk_f32 v59, v59, 0x3c800000, v185
	v_mul_f32_e32 v66, 0x4b800000, v59
	v_cmp_gt_f32_e32 vcc, s86, v59
	v_mov_b32_e32 v151, v157
	v_mov_b32_e32 v149, v157
	v_cndmask_b32_e32 v59, v59, v66, vcc
	v_rsq_f32_e32 v66, v59
	v_mul_f32_e32 v59, 0x3e38aa3b, v75
	v_cvt_pk_bf16_f32 v59, v67, v59
	v_mul_f32_e32 v67, 0x3e38aa3b, v77
	v_mul_f32_e32 v70, 0x45800000, v66
	v_cndmask_b32_e32 v66, v66, v70, vcc
	v_mul_f32_e32 v68, v66, v68
	v_mul_f32_e32 v44, v44, v68
	v_mul_f32_e32 v68, v66, v69
	v_mul_f32_e32 v45, v45, v68
	v_mul_f32_e32 v68, v45, v45
	v_mul_f32_e32 v69, v66, v76
	v_fmac_f32_e32 v68, v44, v44
	v_mul_f32_e32 v46, v46, v69
	v_mul_f32_e32 v69, v66, v80
	v_fmac_f32_e32 v68, v46, v46
	v_mul_f32_e32 v47, v47, v69
	v_mul_f32_e32 v69, v66, v84
	v_fmac_f32_e32 v68, v47, v47
	v_mul_f32_e32 v40, v40, v69
	v_mul_f32_e32 v69, v66, v85
	v_fmac_f32_e32 v68, v40, v40
	v_mul_f32_e32 v41, v41, v69
	v_mul_f32_e32 v69, v66, v86
	v_fmac_f32_e32 v68, v41, v41
	v_mul_f32_e32 v42, v42, v69
	v_mul_f32_e32 v69, v66, v87
	v_fmac_f32_e32 v68, v42, v42
	v_mul_f32_e32 v43, v43, v69
	v_mul_f32_e32 v63, v66, v63
	v_fmac_f32_e32 v68, v43, v43
	v_mul_f32_e32 v36, v36, v63
	v_mul_f32_e32 v62, v66, v62
	v_fmac_f32_e32 v68, v36, v36
	v_mul_f32_e32 v37, v37, v62
	v_mul_f32_e32 v49, v66, v49
	v_fmac_f32_e32 v68, v37, v37
	v_mul_f32_e32 v38, v38, v49
	v_mul_f32_e32 v48, v66, v48
	v_fmac_f32_e32 v68, v38, v38
	v_mul_f32_e32 v39, v39, v48
	v_mul_f32_e32 v48, v66, v65
	v_fmac_f32_e32 v68, v39, v39
	v_mul_f32_e32 v32, v32, v48
	v_mul_f32_e32 v48, v66, v64
	v_fmac_f32_e32 v68, v32, v32
	v_mul_f32_e32 v33, v33, v48
	v_mul_f32_e32 v48, v66, v51
	v_fmac_f32_e32 v68, v33, v33
	v_mul_f32_e32 v34, v34, v48
	v_mul_f32_e32 v48, v66, v50
	v_fmac_f32_e32 v68, v34, v34
	v_mul_f32_e32 v35, v35, v48
	v_fmac_f32_e32 v68, v35, v35
	ds_bpermute_b32 v48, v158, v68
	v_mul_f32_e32 v49, 0x3e38aa3b, v78
	v_cvt_pk_bf16_f32 v80, v67, v49
	v_mul_f32_e32 v49, 0x3e38aa3b, v79
	v_mul_f32_e32 v50, 0x3e38aa3b, v81
	s_waitcnt lgkmcnt(0)
	v_add_f32_e32 v48, v68, v48
	ds_bpermute_b32 v51, v159, v48
	v_cvt_pk_bf16_f32 v81, v49, v50
	v_mul_f32_e32 v49, 0x3e38aa3b, v82
	v_mul_f32_e32 v50, 0x3e38aa3b, v83
	v_cvt_pk_bf16_f32 v82, v49, v50
	s_waitcnt lgkmcnt(0)
	v_add_f32_e32 v48, v48, v51
	v_mul_f32_e32 v49, 0x4f800000, v48
	v_cmp_gt_f32_e32 vcc, s0, v48
	v_mul_f32_e32 v50, 0x3e38aa3b, v90
	v_mul_f32_e32 v51, 0x3e38aa3b, v61
	v_cndmask_b32_e32 v48, v48, v49, vcc
	v_sqrt_f32_e32 v49, v48
	v_cvt_pk_bf16_f32 v83, v50, v51
	v_mul_f32_e32 v44, 0x3e38aa3b, v44
	v_mul_f32_e32 v45, 0x3e38aa3b, v45
	v_add_u32_e32 v50, -1, v49
	v_fma_f32 v51, -v50, v49, v48
	v_cmp_ge_f32_e64 s[6:7], 0, v51
	v_add_u32_e32 v51, 1, v49
	v_mul_f32_e32 v40, 0x3e38aa3b, v40
	v_cndmask_b32_e64 v50, v49, v50, s[6:7]
	v_fma_f32 v49, -v51, v49, v48
	v_cmp_lt_f32_e64 s[6:7], 0, v49
	v_mul_f32_e32 v41, 0x3e38aa3b, v41
	v_mul_f32_e32 v36, 0x3e38aa3b, v36
	v_cndmask_b32_e64 v49, v50, v51, s[6:7]
	v_mul_f32_e32 v50, 0x37800000, v49
	v_cndmask_b32_e32 v49, v49, v50, vcc
	v_cmp_class_f32_e32 vcc, v48, v91
	v_mul_f32_e32 v37, 0x3e38aa3b, v37
	v_mul_f32_e32 v32, 0x3e38aa3b, v32
	v_cndmask_b32_e32 v48, v49, v48, vcc
	s_cselect_b64 vcc, -1, 0
	v_mul_f32_e32 v33, 0x3e38aa3b, v33
	v_cndmask_b32_e32 v199, 0, v3, vcc
	v_cvt_pk_bf16_f32 v92, v44, v45
	v_mul_f32_e32 v44, 0x3e38aa3b, v46
	v_mul_f32_e32 v45, 0x3e38aa3b, v47
	v_cvt_pk_bf16_f32 v93, v44, v45
	v_cvt_pk_bf16_f32 v94, v40, v41
	v_mul_f32_e32 v40, 0x3e38aa3b, v42
	v_mul_f32_e32 v41, 0x3e38aa3b, v43
	v_cvt_pk_bf16_f32 v95, v40, v41
	v_cvt_pk_bf16_f32 v100, v36, v37
	v_mul_f32_e32 v36, 0x3e38aa3b, v38
	v_mul_f32_e32 v37, 0x3e38aa3b, v39
	v_cvt_pk_bf16_f32 v101, v36, v37
	v_cvt_pk_bf16_f32 v102, v32, v33
	v_mul_f32_e32 v32, 0x3e38aa3b, v34
	v_sub_u32_e32 v33, v162, v165
	v_lshlrev_b32_e32 v197, 5, v199
	v_cvt_f32_i32_e32 v34, v33
	v_mul_f32_e32 v35, 0x3e38aa3b, v35
	v_cvt_pk_bf16_f32 v103, v32, v35
	v_mul_u32_u24_e32 v3, 0x220, v162
	v_sub_u32_e32 v198, v33, v197
	v_lshlrev_b32_e32 v32, 7, v163
	v_lshlrev_b32_e32 v33, 6, v199
	v_add3_u32 v3, v3, v32, v33
	v_or_b32_e32 v2, v3, v2
	v_readlane_b32 s0, v255, 22
	v_mul_f32_e32 v48, v60, v48
	v_mul_f32_e32 v48, 0x3e38aa3b, v48
	v_add_u32_e32 v163, s0, v2
	v_add3_u32 v2, v164, v197, v162
	v_mul_u32_u24_e32 v2, 0x90, v2
	v_max_f32_e32 v168, v160, v48
	v_add3_u32 v164, v2, v0, 0
	v_mov_b32_e32 v2, v1
	v_mov_b32_e32 v3, v1
	v_mul_f32_e32 v169, v170, v34
	v_fmac_f32_e32 v161, v170, v34
	v_fmac_f32_e32 v166, v170, v34
	v_fmac_f32_e32 v167, v170, v34
	v_fmac_f32_e32 v168, v170, v34
	v_mov_b32_e32 v0, v1
	v_mov_b64_e32 v[34:35], v[2:3]
	v_mov_b64_e32 v[38:39], v[2:3]
	v_mov_b64_e32 v[42:43], v[2:3]
	v_mov_b64_e32 v[46:47], v[2:3]
	v_mov_b64_e32 v[50:51], v[2:3]
	v_mov_b64_e32 v[62:63], v[2:3]
	v_mov_b64_e32 v[66:67], v[2:3]
	v_mov_b64_e32 v[70:71], v[2:3]
	v_mov_b64_e32 v[74:75], v[2:3]
	v_mov_b64_e32 v[78:79], v[2:3]
	v_mov_b64_e32 v[86:87], v[2:3]
	v_mov_b64_e32 v[90:91], v[2:3]
	v_mov_b64_e32 v[98:99], v[2:3]
	v_mov_b64_e32 v[106:107], v[2:3]
	v_mov_b64_e32 v[110:111], v[2:3]
	v_mov_b64_e32 v[114:115], v[2:3]
	s_mov_b32 s11, 0
	v_mul_f32_e32 v171, 0x43000000, v170
	v_mul_f32_e32 v172, 0x42fe0000, v170
	v_mul_f32_e32 v173, 0x42fc0000, v170
	v_mul_f32_e32 v174, 0x42fa0000, v170
	v_mul_f32_e32 v175, 0x42e00000, v170
	v_mul_f32_e32 v176, 0x42de0000, v170
	v_mul_f32_e32 v177, 0x42dc0000, v170
	v_mul_f32_e32 v178, 0x42da0000, v170
	v_mul_f32_e32 v179, 0x43100000, v170
	v_mul_f32_e32 v180, 0x430f0000, v170
	v_mul_f32_e32 v181, 0x430e0000, v170
	v_mul_f32_e32 v182, 0x430d0000, v170
	v_mul_f32_e32 v183, 0x43200000, v170
	v_mul_f32_e32 v190, 0x431f0000, v170
	v_mul_f32_e32 v191, 0x431e0000, v170
	v_mul_f32_e32 v192, 0x431d0000, v170
	v_mul_f32_e32 v193, 0x43300000, v170
	v_mul_f32_e32 v194, 0x432f0000, v170
	v_mul_f32_e32 v195, 0x432e0000, v170
	v_mul_f32_e32 v196, 0x432d0000, v170
	v_mov_b32_e32 v162, 0
	s_mov_b64 s[8:9], 0
	s_mov_b32 s12, 0
	v_mov_b64_e32 v[32:33], v[0:1]
	v_mov_b64_e32 v[36:37], v[0:1]
	v_mov_b64_e32 v[40:41], v[0:1]
	v_mov_b64_e32 v[44:45], v[0:1]
	v_mov_b64_e32 v[48:49], v[0:1]
	v_mov_b64_e32 v[60:61], v[0:1]
	v_mov_b64_e32 v[64:65], v[0:1]
	v_mov_b64_e32 v[68:69], v[0:1]
	v_mov_b64_e32 v[72:73], v[0:1]
	v_mov_b64_e32 v[76:77], v[0:1]
	v_mov_b64_e32 v[84:85], v[0:1]
	v_mov_b64_e32 v[88:89], v[0:1]
	v_mov_b64_e32 v[96:97], v[0:1]
	v_mov_b64_e32 v[104:105], v[0:1]
	v_mov_b64_e32 v[108:109], v[0:1]
	v_mov_b64_e32 v[112:113], v[0:1]
	v_mov_b32_e32 v2, 0
	v_mov_b32_e32 v3, 0
	v_mov_b32_e32 v0, 0
	v_readlane_b32 s53, v252, 39
	v_readlane_b32 s54, v252, 40
	v_readlane_b32 s55, v252, 41
	v_readlane_b32 s56, v252, 42
	v_readlane_b32 s57, v252, 43
	v_readlane_b32 s60, v252, 46
	v_readlane_b32 s61, v252, 47
	v_readlane_b32 s62, v252, 48
	v_readlane_b32 s63, v252, 49
	v_readlane_b32 s64, v252, 50
	v_readlane_b32 s65, v252, 51
	v_readlane_b32 s66, v252, 52
	v_readlane_b32 s67, v252, 53
	s_branch .LBB0_372
